# baseline (speedup 1.0000x reference)
; __global__ void __launch_bounds__(NTHREADS, 2) fwd_megakernel(Params p_arg) {
;     ...
;   if (xb.local_ok) {
; #pragma unroll 1
;     for (int i = 0; i < (int)xb.x * XCC_SKEW_SLEEPS; ++i) __builtin_amdgcn_s_sleep(127);
;   }
.LBB0_110:
	s_or_b64 exec, exec, s[4:5]
	s_cmpk_gt_u32 s16, 0xffff
	s_cselect_b64 s[4:5], -1, 0
	s_cmp_gt_i32 s7, 0
	s_cselect_b64 s[0:1], -1, 0
	v_writelane_b32 v255, s4, 16
	s_and_b64 s[0:1], s[4:5], s[0:1]
	s_mov_b32 s29, 0
	v_writelane_b32 v255, s5, 17
	s_and_b64 vcc, exec, s[0:1]
	s_barrier
	s_cbranch_vccz .LBB0_113
	s_mul_i32 s0, s7, 3
	s_max_i32 s0, s0, 1
.LBB0_112:
	s_add_i32 s0, s0, -1
	s_cmp_lg_u32 s0, 0
	s_sleep 0x40
	s_cbranch_scc1 .LBB0_112
